# baseline (speedup 1.0000x reference)
; #define SBAR() __builtin_amdgcn_sched_barrier(0)
; #define HBAR(n) do { asm volatile("s_waitcnt vmcnt(" #n ") lgkmcnt(0)" ::: "memory"); __builtin_amdgcn_s_barrier(); asm volatile("" ::: "memory"); } while (0)
; #define RD2(S, k, D0) do { S##l##k = tr_read<v_rd_off(D0, k, 0)>(vb); S##h##k = tr_read<v_rd_off(D0, k, 1)>(vb); } while (0)
; #define PVB(X, Y, D0, D1) do { LW(6); MF(X, 0, D0, pa0); SBAR(); RD2(Y, 0, D1); LW(6); MF(X, 1, D0, pa1); SBAR(); RD2(Y, 1, D1); \
;     LW(6); MF(X, 2, D0, pa2); SBAR(); RD2(Y, 2, D1); LW(6); MF(X, 3, D0, pa3); SBAR(); RD2(Y, 3, D1); } while (0)
; __device__ __forceinline__ void finishSM(f32x16& p0, f32x16& p1, float alpha, float& l_reg, bf16x8& pa0, bf16x8& pa1, bf16x8& pa2, bf16x8& pa3) {
;     float ps = 0; for (int r = 0; r < 16; ++r) ps += p0[r]; for (int r = 0; r < 16; ++r) ps += p1[r];
;     { auto rr = __builtin_amdgcn_permlane32_swap(__float_as_uint(ps), __float_as_uint(ps), false, false);
;       ps = __uint_as_float(rr[0]) + __uint_as_float(rr[1]); }
;     l_reg = l_reg * alpha + ps;
;     ...
;     PK4(p0, 0, pa0); PK4(p0, 8, pa1); PK4(p1, 0, pa2); PK4(p1, 8, pa3);
;     ...
; }
; __device__ __forceinline__ void attn_dense_body(const bf16_t* __restrict__ Qb, const bf16_t* __restrict__ Kh, const bf16_t* __restrict__ Vh,
;                                                 float* __restrict__ Ob, int seq, char* lds, LAS unsigned char* lds3, const int tid) {
;     ...
;         const int vb = vb0 + b * (int)SHM_V;
;         s16x4 Al0, Ah0, Al1, Ah1, Al2, Ah2, Al3, Ah3, Bl0, Bh0, Bl1, Bh1, Bl2, Bh2, Bl3, Bh3;
;     ...
;         HBAR(6);
;         SBAR();
;         {
;     ...
;           __builtin_amdgcn_s_setprio(1);
;           RD2(A, 0, 0); RD2(A, 1, 0); RD2(A, 2, 0); RD2(A, 3, 0);
;           PVB(A, B, 0, 1); PVB(B, A, 1, 2); PVB(A, B, 2, 3); PVB(B, A, 3, 4); PVB(A, B, 4, 5); PVB(B, A, 5, 6); PVB(A, B, 6, 7);
.Lat_cont:
	v_add_f32_e32 v245, v245, v0
	v_add_f32_e32 v229, v229, v14
	v_cvt_pk_bf16_f32 v2, v160, v161
	v_cvt_pk_bf16_f32 v3, v162, v163
	v_cvt_pk_bf16_f32 v4, v168, v169
	v_cvt_pk_bf16_f32 v5, v170, v171
	v_cvt_pk_bf16_f32 v6, v176, v177
	v_cvt_pk_bf16_f32 v7, v178, v179
	v_cvt_pk_bf16_f32 v8, v184, v185
	v_cvt_pk_bf16_f32 v9, v186, v187
	v_cvt_pk_bf16_f32 v10, v164, v165
	v_cvt_pk_bf16_f32 v11, v166, v167
	v_cvt_pk_bf16_f32 v12, v172, v173
	v_cvt_pk_bf16_f32 v13, v174, v175
	v_cvt_pk_bf16_f32 v152, v180, v181
	v_cvt_pk_bf16_f32 v153, v182, v183
	v_cvt_pk_bf16_f32 v154, v188, v189
	v_cvt_pk_bf16_f32 v155, v190, v191
	v_lshl_add_u32 v14, s91, 15, v247
	v_lshl_add_u32 v232, s99, 14, v246
	v_add_u32_e32 v0, v239, v232
	v_xad_u32 v15, v239, 64, v232
	v_xad_u32 v231, v239, s60, v232
	s_movk_i32 s0, 0xc0
	v_xad_u32 v232, v239, s0, v232
	ds_read_b64_tr_b16 v[160:161], v14 offset:0
	ds_read_b64_tr_b16 v[162:163], v14 offset:8192
	ds_read_b64_tr_b16 v[164:165], v14 offset:256
	ds_read_b64_tr_b16 v[166:167], v14 offset:8448
	ds_read_b64_tr_b16 v[168:169], v14 offset:512
	ds_read_b64_tr_b16 v[170:171], v14 offset:8704
	ds_read_b64_tr_b16 v[172:173], v14 offset:768
	ds_read_b64_tr_b16 v[174:175], v14 offset:8960
	ds_read_b64_tr_b16 v[176:177], v14 offset:1024
	ds_read_b64_tr_b16 v[178:179], v14 offset:9216
	ds_read_b64_tr_b16 v[180:181], v14 offset:1280
	ds_read_b64_tr_b16 v[182:183], v14 offset:9472
	ds_read_b64_tr_b16 v[184:185], v14 offset:1536
	ds_read_b64_tr_b16 v[186:187], v14 offset:9728
	ds_read_b64_tr_b16 v[188:189], v14 offset:1792
	ds_read_b64_tr_b16 v[190:191], v14 offset:9984
	ds_read_b64_tr_b16 v[156:157], v14 offset:2048
	ds_read_b64_tr_b16 v[158:159], v14 offset:10240
	ds_read_b64_tr_b16 v[224:225], v14 offset:2304
	ds_read_b64_tr_b16 v[226:227], v14 offset:10496
	ds_read_b64_tr_b16 v[234:235], v14 offset:2560
	ds_read_b64_tr_b16 v[236:237], v14 offset:10752
	ds_read_b64_tr_b16 v[248:249], v14 offset:2816
	ds_read_b64_tr_b16 v[250:251], v14 offset:11008
	s_waitcnt vmcnt(6)
	s_barrier
	s_setprio 1
	s_waitcnt lgkmcnt(15)
	v_mfma_f32_16x16x32_bf16 v[16:19], v[2:5], v[160:163], v[16:19]
	v_mfma_f32_16x16x32_bf16 v[80:83], v[10:13], v[160:163], v[80:83]
	s_waitcnt lgkmcnt(15)
	v_mfma_f32_16x16x32_bf16 v[20:23], v[2:5], v[164:167], v[20:23]
	ds_read_b64_tr_b16 v[160:161], v14 offset:3072
	v_mfma_f32_16x16x32_bf16 v[84:87], v[10:13], v[164:167], v[84:87]
	ds_read_b64_tr_b16 v[162:163], v14 offset:11264
	s_waitcnt lgkmcnt(15)
	v_mfma_f32_16x16x32_bf16 v[24:27], v[2:5], v[168:171], v[24:27]
	ds_read_b64_tr_b16 v[164:165], v14 offset:3328
	v_mfma_f32_16x16x32_bf16 v[88:91], v[10:13], v[168:171], v[88:91]
	ds_read_b64_tr_b16 v[166:167], v14 offset:11520
	s_waitcnt lgkmcnt(15)
	v_mfma_f32_16x16x32_bf16 v[28:31], v[2:5], v[172:175], v[28:31]
	ds_read_b64_tr_b16 v[168:169], v14 offset:3584
	v_mfma_f32_16x16x32_bf16 v[92:95], v[10:13], v[172:175], v[92:95]
	ds_read_b64_tr_b16 v[170:171], v14 offset:11776
	s_waitcnt lgkmcnt(15)
	v_mfma_f32_16x16x32_bf16 v[32:35], v[2:5], v[176:179], v[32:35]
	ds_read_b64_tr_b16 v[172:173], v14 offset:3840
	v_mfma_f32_16x16x32_bf16 v[96:99], v[10:13], v[176:179], v[96:99]
	ds_read_b64_tr_b16 v[174:175], v14 offset:12032
	s_waitcnt lgkmcnt(15)
	v_mfma_f32_16x16x32_bf16 v[36:39], v[2:5], v[180:183], v[36:39]
	ds_read_b64_tr_b16 v[176:177], v14 offset:16384
	v_mfma_f32_16x16x32_bf16 v[100:103], v[10:13], v[180:183], v[100:103]
	ds_read_b64_tr_b16 v[178:179], v14 offset:24576
	s_waitcnt lgkmcnt(15)
	v_mfma_f32_16x16x32_bf16 v[40:43], v[2:5], v[184:187], v[40:43]
	ds_read_b64_tr_b16 v[180:181], v14 offset:16640
	v_mfma_f32_16x16x32_bf16 v[104:107], v[10:13], v[184:187], v[104:107]
	ds_read_b64_tr_b16 v[182:183], v14 offset:24832
	s_waitcnt lgkmcnt(15)
	v_mfma_f32_16x16x32_bf16 v[44:47], v[2:5], v[188:191], v[44:47]
	ds_read_b64_tr_b16 v[184:185], v14 offset:16896
	v_mfma_f32_16x16x32_bf16 v[108:111], v[10:13], v[188:191], v[108:111]
	ds_read_b64_tr_b16 v[186:187], v14 offset:25088
	s_waitcnt lgkmcnt(15)
	v_mfma_f32_16x16x32_bf16 v[48:51], v[2:5], v[156:159], v[48:51]
	ds_read_b64_tr_b16 v[188:189], v14 offset:17152
	v_mfma_f32_16x16x32_bf16 v[112:115], v[10:13], v[156:159], v[112:115]
	ds_read_b64_tr_b16 v[190:191], v14 offset:25344
	s_waitcnt lgkmcnt(15)
	v_mfma_f32_16x16x32_bf16 v[52:55], v[2:5], v[224:227], v[52:55]
	v_mfma_f32_16x16x32_bf16 v[116:119], v[10:13], v[224:227], v[116:119]
	s_waitcnt lgkmcnt(15)
	v_mfma_f32_16x16x32_bf16 v[56:59], v[2:5], v[234:237], v[56:59]
	v_mfma_f32_16x16x32_bf16 v[120:123], v[10:13], v[234:237], v[120:123]
	s_waitcnt lgkmcnt(15)
	v_mfma_f32_16x16x32_bf16 v[60:63], v[2:5], v[248:251], v[60:63]
	v_mfma_f32_16x16x32_bf16 v[124:127], v[10:13], v[248:251], v[124:127]
	s_waitcnt lgkmcnt(14)
	v_mfma_f32_16x16x32_bf16 v[64:67], v[2:5], v[160:163], v[64:67]
	v_mfma_f32_16x16x32_bf16 v[128:131], v[10:13], v[160:163], v[128:131]
	s_waitcnt lgkmcnt(12)
	v_mfma_f32_16x16x32_bf16 v[68:71], v[2:5], v[164:167], v[68:71]
	ds_read_b64_tr_b16 v[160:161], v14 offset:17408
	v_mfma_f32_16x16x32_bf16 v[132:135], v[10:13], v[164:167], v[132:135]
	ds_read_b64_tr_b16 v[162:163], v14 offset:25600
	s_waitcnt lgkmcnt(12)
	v_mfma_f32_16x16x32_bf16 v[72:75], v[2:5], v[168:171], v[72:75]
	ds_read_b64_tr_b16 v[164:165], v14 offset:17664
	v_mfma_f32_16x16x32_bf16 v[136:139], v[10:13], v[168:171], v[136:139]
	ds_read_b64_tr_b16 v[166:167], v14 offset:25856
	s_waitcnt lgkmcnt(12)
	v_mfma_f32_16x16x32_bf16 v[76:79], v[2:5], v[172:175], v[76:79]
	ds_read_b64_tr_b16 v[168:169], v14 offset:17920
	v_mfma_f32_16x16x32_bf16 v[140:143], v[10:13], v[172:175], v[140:143]
	ds_read_b64_tr_b16 v[170:171], v14 offset:26112
	s_waitcnt lgkmcnt(12)
; #define SBAR() __builtin_amdgcn_sched_barrier(0)
; #define KM(d0, B0, B1) do { p0 = __builtin_amdgcn_mfma_f32_32x32x16_bf16(B0, qr[d0], p0, 0, 0, 0); p1 = __builtin_amdgcn_mfma_f32_32x32x16_bf16(B1, qr[d0], p1, 0, 0, 0); } while (0)
; #define HBAR(n) do { asm volatile("s_waitcnt vmcnt(" #n ") lgkmcnt(0)" ::: "memory"); __builtin_amdgcn_s_barrier(); asm volatile("" ::: "memory"); } while (0)
; #define LW(n) do { asm volatile("s_waitcnt lgkmcnt(" #n ")" ::: "memory"); SBAR(); } while (0)
; #define RD2(S, k, D0) do { S##l##k = tr_read<v_rd_off(D0, k, 0)>(vb); S##h##k = tr_read<v_rd_off(D0, k, 1)>(vb); } while (0)
; #define LW(n) do { asm volatile("s_waitcnt lgkmcnt(" #n ")" ::: "memory"); SBAR(); } while (0)
; __device__ __forceinline__ void attn_dense_body(const bf16_t* __restrict__ Qb, const bf16_t* __restrict__ Kh, const bf16_t* __restrict__ Vh,
;                                                 float* __restrict__ Ob, int seq, char* lds, LAS unsigned char* lds3, const int tid) {
;     ...
;           __builtin_amdgcn_s_setprio(1);
;           RD2(A, 0, 0); RD2(A, 1, 0); RD2(A, 2, 0); RD2(A, 3, 0);
;           PVB(A, B, 0, 1); PVB(B, A, 1, 2); PVB(A, B, 2, 3); PVB(B, A, 3, 4); PVB(A, B, 4, 5); PVB(B, A, 5, 6); PVB(A, B, 6, 7);
;           const int kadr = (int)(uintptr_t)K_lds + b1 * (int)SHM_K + r32 * 256; int kt = (hi * 16) ^ ((r32 & 7) << 4);
;           asm volatile("" : "+v"(kt));
;           bf16x8 k0a, k0b, k1a, k1b, k2a, k2b;
;     ...
;           LW(6); MF(B, 0, 7, pa0); SBAR(); KRD(0, k0a, k0b);
;           LW(6); MF(B, 1, 7, pa1); SBAR(); KRD(1, k1a, k1b);
;           LW(6); MF(B, 2, 7, pa2); SBAR(); KRD(2, k2a, k2b);
;           LW(6); MF(B, 3, 7, pa3); SBAR();
;           LW(4); p0 = __builtin_amdgcn_mfma_f32_32x32x16_bf16(k0a, qr[0], nm, 0, 0, 0); p1 = __builtin_amdgcn_mfma_f32_32x32x16_bf16(k0b, qr[0], nm, 0, 0, 0); SBAR(); KRD(3, k0a, k0b);
;           LW(4); KM(1, k1a, k1b); SBAR(); KRD(4, k1a, k1b);
;           LW(4); KM(2, k2a, k2b); SBAR(); KRD(5, k2a, k2b);
;           LW(4); KM(3, k0a, k0b); SBAR(); KRD(6, k0a, k0b);
;           LW(4); KM(4, k1a, k1b); SBAR(); KRD(7, k1a, k1b);
;           LW(4); KM(5, k2a, k2b); SBAR();
;           LW(2); KM(6, k0a, k0b); SBAR();
;           LW(0); KM(7, k1a, k1b);
;           __builtin_amdgcn_s_setprio(0);
;     ...
;         }
;     ...
;         HBAR(0);
;         { const int t_ = b; b = b1; b1 = b2; b2 = t_; }
;     }
	v_mfma_f32_16x16x32_bf16 v[16:19], v[6:9], v[176:179], v[16:19]
	ds_read_b64_tr_b16 v[172:173], v14 offset:18176
	v_mfma_f32_16x16x32_bf16 v[80:83], v[152:155], v[176:179], v[80:83]
	ds_read_b64_tr_b16 v[174:175], v14 offset:26368
	s_waitcnt lgkmcnt(12)
	v_mfma_f32_16x16x32_bf16 v[20:23], v[6:9], v[180:183], v[20:23]
	ds_read_b64_tr_b16 v[176:177], v14 offset:18432
	v_mfma_f32_16x16x32_bf16 v[84:87], v[152:155], v[180:183], v[84:87]
	ds_read_b64_tr_b16 v[178:179], v14 offset:26624
	s_waitcnt lgkmcnt(12)
	v_mfma_f32_16x16x32_bf16 v[24:27], v[6:9], v[184:187], v[24:27]
	ds_read_b64_tr_b16 v[180:181], v14 offset:18688
	v_mfma_f32_16x16x32_bf16 v[88:91], v[152:155], v[184:187], v[88:91]
	ds_read_b64_tr_b16 v[182:183], v14 offset:26880
	s_waitcnt lgkmcnt(12)
	v_mfma_f32_16x16x32_bf16 v[28:31], v[6:9], v[188:191], v[28:31]
	ds_read_b64_tr_b16 v[184:185], v14 offset:18944
	v_mfma_f32_16x16x32_bf16 v[92:95], v[152:155], v[188:191], v[92:95]
	ds_read_b64_tr_b16 v[186:187], v14 offset:27136
	s_waitcnt lgkmcnt(12)
	v_mfma_f32_16x16x32_bf16 v[32:35], v[6:9], v[160:163], v[32:35]
	ds_read_b64_tr_b16 v[188:189], v14 offset:19200
	v_mfma_f32_16x16x32_bf16 v[96:99], v[152:155], v[160:163], v[96:99]
	ds_read_b64_tr_b16 v[190:191], v14 offset:27392
	s_waitcnt lgkmcnt(12)
	v_mfma_f32_16x16x32_bf16 v[36:39], v[6:9], v[164:167], v[36:39]
	ds_read_b64_tr_b16 v[160:161], v14 offset:19456
	v_mfma_f32_16x16x32_bf16 v[100:103], v[152:155], v[164:167], v[100:103]
	ds_read_b64_tr_b16 v[162:163], v14 offset:27648
	s_waitcnt lgkmcnt(12)
	v_mfma_f32_16x16x32_bf16 v[40:43], v[6:9], v[168:171], v[40:43]
	ds_read_b64_tr_b16 v[164:165], v14 offset:19712
	v_mfma_f32_16x16x32_bf16 v[104:107], v[152:155], v[168:171], v[104:107]
	ds_read_b64_tr_b16 v[166:167], v14 offset:27904
	s_waitcnt lgkmcnt(12)
	v_mfma_f32_16x16x32_bf16 v[44:47], v[6:9], v[172:175], v[44:47]
	ds_read_b64_tr_b16 v[168:169], v14 offset:19968
	v_mfma_f32_16x16x32_bf16 v[108:111], v[152:155], v[172:175], v[108:111]
	ds_read_b64_tr_b16 v[170:171], v14 offset:28160
	s_waitcnt lgkmcnt(12)
	v_mfma_f32_16x16x32_bf16 v[48:51], v[6:9], v[176:179], v[48:51]
	ds_read_b64_tr_b16 v[172:173], v14 offset:20224
	v_mfma_f32_16x16x32_bf16 v[112:115], v[152:155], v[176:179], v[112:115]
	ds_read_b64_tr_b16 v[174:175], v14 offset:28416
	s_waitcnt lgkmcnt(12)
	v_mfma_f32_16x16x32_bf16 v[52:55], v[6:9], v[180:183], v[52:55]
	v_mfma_f32_16x16x32_bf16 v[116:119], v[152:155], v[180:183], v[116:119]
	s_waitcnt lgkmcnt(10)
	v_mfma_f32_16x16x32_bf16 v[56:59], v[6:9], v[184:187], v[56:59]
	v_mfma_f32_16x16x32_bf16 v[120:123], v[152:155], v[184:187], v[120:123]
	s_waitcnt lgkmcnt(8)
	v_mfma_f32_16x16x32_bf16 v[60:63], v[6:9], v[188:191], v[60:63]
	v_mfma_f32_16x16x32_bf16 v[124:127], v[152:155], v[188:191], v[124:127]
	s_waitcnt lgkmcnt(6)
	v_mfma_f32_16x16x32_bf16 v[64:67], v[6:9], v[160:163], v[64:67]
	v_mfma_f32_16x16x32_bf16 v[128:131], v[152:155], v[160:163], v[128:131]
	ds_read_b128 v[156:159], v0 offset:0
	s_waitcnt lgkmcnt(5)
	v_mfma_f32_16x16x32_bf16 v[68:71], v[6:9], v[164:167], v[68:71]
	v_mfma_f32_16x16x32_bf16 v[132:135], v[152:155], v[164:167], v[132:135]
	ds_read_b128 v[224:227], v15 offset:0
	s_waitcnt lgkmcnt(4)
	v_mfma_f32_16x16x32_bf16 v[72:75], v[6:9], v[168:171], v[72:75]
	v_mfma_f32_16x16x32_bf16 v[136:139], v[152:155], v[168:171], v[136:139]
	ds_read_b128 v[234:237], v231 offset:0
	s_waitcnt lgkmcnt(3)
	v_mfma_f32_16x16x32_bf16 v[76:79], v[6:9], v[172:175], v[76:79]
	v_mfma_f32_16x16x32_bf16 v[140:143], v[152:155], v[172:175], v[140:143]
	ds_read_b128 v[248:251], v232 offset:0
	ds_read_b128 v[2:5], v0 offset:4096
	ds_read_b128 v[6:9], v15 offset:4096
	ds_read_b128 v[10:13], v231 offset:4096
	ds_read_b128 v[152:155], v232 offset:4096
	s_waitcnt lgkmcnt(7)
	v_mfma_f32_16x16x32_bf16 v[160:163], v[156:159], v[192:195], v[144:147]
	v_mfma_f32_16x16x32_bf16 v[164:167], v[156:159], v[208:211], v[148:151]
	ds_read_b128 v[156:159], v0 offset:8192
	s_waitcnt lgkmcnt(7)
	v_mfma_f32_16x16x32_bf16 v[160:163], v[224:227], v[196:199], v[160:163]
	v_mfma_f32_16x16x32_bf16 v[164:167], v[224:227], v[212:215], v[164:167]
	ds_read_b128 v[224:227], v15 offset:8192
	s_waitcnt lgkmcnt(7)
	v_mfma_f32_16x16x32_bf16 v[160:163], v[234:237], v[200:203], v[160:163]
	v_mfma_f32_16x16x32_bf16 v[164:167], v[234:237], v[216:219], v[164:167]
	ds_read_b128 v[234:237], v231 offset:8192
	s_waitcnt lgkmcnt(7)
	v_mfma_f32_16x16x32_bf16 v[160:163], v[248:251], v[204:207], v[160:163]
	v_mfma_f32_16x16x32_bf16 v[164:167], v[248:251], v[220:223], v[164:167]
	ds_read_b128 v[248:251], v232 offset:8192
	s_waitcnt lgkmcnt(7)
	v_mfma_f32_16x16x32_bf16 v[168:171], v[2:5], v[192:195], v[144:147]
	v_mfma_f32_16x16x32_bf16 v[172:175], v[2:5], v[208:211], v[148:151]
	ds_read_b128 v[2:5], v0 offset:12288
	s_waitcnt lgkmcnt(7)
	v_mfma_f32_16x16x32_bf16 v[168:171], v[6:9], v[196:199], v[168:171]
	v_mfma_f32_16x16x32_bf16 v[172:175], v[6:9], v[212:215], v[172:175]
	ds_read_b128 v[6:9], v15 offset:12288
	s_waitcnt lgkmcnt(7)
	v_mfma_f32_16x16x32_bf16 v[168:171], v[10:13], v[200:203], v[168:171]
	v_mfma_f32_16x16x32_bf16 v[172:175], v[10:13], v[216:219], v[172:175]
	ds_read_b128 v[10:13], v231 offset:12288
	s_waitcnt lgkmcnt(7)
	v_mfma_f32_16x16x32_bf16 v[168:171], v[152:155], v[204:207], v[168:171]
	v_mfma_f32_16x16x32_bf16 v[172:175], v[152:155], v[220:223], v[172:175]
	ds_read_b128 v[152:155], v232 offset:12288
	s_waitcnt lgkmcnt(7)
	v_mfma_f32_16x16x32_bf16 v[176:179], v[156:159], v[192:195], v[144:147]
	v_mfma_f32_16x16x32_bf16 v[180:183], v[156:159], v[208:211], v[148:151]
	s_waitcnt lgkmcnt(6)
	v_mfma_f32_16x16x32_bf16 v[176:179], v[224:227], v[196:199], v[176:179]
	v_mfma_f32_16x16x32_bf16 v[180:183], v[224:227], v[212:215], v[180:183]
	s_waitcnt lgkmcnt(5)
	v_mfma_f32_16x16x32_bf16 v[176:179], v[234:237], v[200:203], v[176:179]
	v_mfma_f32_16x16x32_bf16 v[180:183], v[234:237], v[216:219], v[180:183]
	s_waitcnt lgkmcnt(4)
	v_mfma_f32_16x16x32_bf16 v[176:179], v[248:251], v[204:207], v[176:179]
	v_mfma_f32_16x16x32_bf16 v[180:183], v[248:251], v[220:223], v[180:183]
	s_waitcnt lgkmcnt(3)
	v_mfma_f32_16x16x32_bf16 v[184:187], v[2:5], v[192:195], v[144:147]
	v_mfma_f32_16x16x32_bf16 v[188:191], v[2:5], v[208:211], v[148:151]
	s_waitcnt lgkmcnt(2)
	v_mfma_f32_16x16x32_bf16 v[184:187], v[6:9], v[196:199], v[184:187]
	v_mfma_f32_16x16x32_bf16 v[188:191], v[6:9], v[212:215], v[188:191]
	s_waitcnt lgkmcnt(1)
	v_mfma_f32_16x16x32_bf16 v[184:187], v[10:13], v[200:203], v[184:187]
	v_mfma_f32_16x16x32_bf16 v[188:191], v[10:13], v[216:219], v[188:191]
	s_waitcnt lgkmcnt(0)
	v_mfma_f32_16x16x32_bf16 v[184:187], v[152:155], v[204:207], v[184:187]
	v_mfma_f32_16x16x32_bf16 v[188:191], v[152:155], v[220:223], v[188:191]
	s_setprio 0
	s_waitcnt vmcnt(0) lgkmcnt(0)
	s_barrier
	s_cmp_eq_u32 s15, s89
	s_cbranch_scc1 .Lat_done
	s_mov_b32 s0, s99
	s_mov_b32 s99, s10
	s_mov_b32 s10, s91
	s_branch .Lat_loop
